# convert (k=0 path): contiguous run of tiles per workgroup instead of stride-256 assignment; init_phase 12 loads in flight
# speedup vs baseline: 1.0016x; 1.0016x over previous
; #define LAS __attribute__((address_space(3)))
; __device__ __forceinline__ unsigned xb_add(unsigned* p, unsigned v) { return __hip_atomic_fetch_add(p, v, __ATOMIC_RELAXED, __HIP_MEMORY_SCOPE_AGENT); }
; __device__ __forceinline__ unsigned xb_xcc_id() { return (unsigned)__builtin_amdgcn_s_getreg((3 << 11) | 20) & 0xFu; }
; __device__ __forceinline__ XcdBarrier xcd_barrier_post(unsigned* bar, volatile LAS unsigned* st) {
;     XcdBarrier b; b.bar = bar; b.x = xb_xcc_id(); b.st = st;
;     if (threadIdx.x == 0) (void)xb_add(&bar[XB_XCNT(b.x)], 1u);
;     return b;
; }
; __global__ void __launch_bounds__(NTHREADS) mega(Args args) {
;     extern __shared__ __attribute__((aligned(16))) unsigned char lds_raw[];
;     cg::grid_group grid = cg::this_grid();
;     Frame F;
;     F.lds = (LAS unsigned char*)lds_raw;
;     F.tid = threadIdx.x; F.lane = F.tid & 63; F.wave = __builtin_amdgcn_readfirstlane(F.tid >> 6);
;     F.G = gridDim.x; F.bid = blockIdx.x;
;     volatile LAS unsigned* bst = (volatile LAS unsigned*)(F.lds + LDS_WORK);
;     if (F.tid < 4) bst[F.tid] = 0u;
;     __syncthreads();
;     XcdBarrier xbar = xcd_barrier_post((unsigned*)(args.ws + WS_BAR), bst);
_Z4mega4Args:
	s_mov_b32 s32, 0
	s_mov_b32 s44, s2
	s_add_u32 s2, s0, 0xd0
	s_addc_u32 s3, s1, 0
	v_and_b32_e32 v138, 0x3ff, v0
	v_writelane_b32 v254, s2, 0
	v_readfirstlane_b32 s6, v138
	v_cmp_gt_u32_e32 vcc, 4, v138
	v_writelane_b32 v254, s3, 1
	s_and_saveexec_b64 s[2:3], vcc
	v_lshl_add_u32 v1, v138, 2, 0
	v_add_u32_e32 v1, 0x20000, v1
	v_mov_b32_e32 v2, 0
	ds_write_b32 v1, v2
	s_or_b64 exec, exec, s[2:3]
	s_waitcnt lgkmcnt(0)
	s_barrier
	s_getreg_b32 s2, hwreg(HW_REG_XCC_ID, 0, 4)
	s_and_b32 s2, s2, 15
	v_writelane_b32 v254, s2, 2
	v_cmp_eq_u32_e64 s[4:5], 0, v138
	s_mov_b64 s[2:3], exec
	s_nop 0
	v_writelane_b32 v254, s4, 3
	s_nop 1
	v_writelane_b32 v254, s5, 4
	s_and_b64 s[4:5], s[2:3], s[4:5]
	s_mov_b64 exec, s[4:5]
	s_cbranch_execz .LBB0_5
	s_mov_b64 s[4:5], exec
	v_mbcnt_lo_u32_b32 v1, s4, 0
	v_mbcnt_hi_u32_b32 v1, s5, v1
	v_cmp_eq_u32_e32 vcc, 0, v1
	s_and_b64 s[8:9], exec, vcc
	s_mov_b64 exec, s[8:9]
	s_cbranch_execz .LBB0_5
	s_bcnt1_i32_b64 s4, s[4:5]
	v_mov_b32_e32 v2, s4
	s_load_dwordx2 s[4:5], s[0:1], 0xb8
	v_readlane_b32 s7, v254, 2
	s_lshl_b32 s7, s7, 8
	s_nop 0
	v_mov_b32_e32 v1, s7
	s_waitcnt lgkmcnt(0)
	global_atomic_add v1, v2, s[4:5] offset:1024

; __device__ __forceinline__ void refresh(Frame& F) { int t = threadIdx.x; asm volatile("" : "+v"(t)); F.tid = t; F.lane = t & 63; F.wave = __builtin_amdgcn_readfirstlane(t >> 6); }
; __device__ __forceinline__ void cvt_pick(const Args& A, const Frame& F, int l, int it, CvtMat& m, int& tt) {
;     constexpr int T_GU = 16 * 44, T_D = 44 * 8, T_IN = 16 * 56, T_SQ = 16 * 8;
;     constexpr int O1 = T_GU, O2 = O1 + T_D, O3 = O2 + T_GU, O4 = O3 + T_D, O5 = O4 + T_IN, O6 = O5 + T_SQ, O7 = O6 + T_SQ;
;     const int sel = (it >= O1) + (it >= O2) + (it >= O3) + (it >= O4) + (it >= O5) + (it >= O6) + (it >= O7);
;     const int inidx = sel == 0 ? 7 : sel == 1 ? 8 : sel == 2 ? 9 : sel == 3 ? 10 : sel == 4 ? 11 : sel == 5 ? 13 : sel == 6 ? 19 : 20;
;     const size_t per_layer = (sel == 0 || sel == 2) ? (size_t)D * 2 * FH : (sel == 1 || sel == 3) ? (size_t)FH * D : sel == 4 ? (size_t)D * PW : (size_t)D * D;
;     const size_t woff = sel == 0 ? WS_WGU1 : sel == 1 ? WS_WD1 : sel == 2 ? WS_WGU2 : sel == 3 ? WS_WD2 : sel == 4 ? WS_WIN : sel == 5 ? WS_WRO : sel == 6 ? WS_WLO : WS_WOUT;
;     m.W = GIN(inidx) + (size_t)l * per_layer; m.Bt = WSB(woff);
;     m.K = (sel == 1 || sel == 3) ? FH : D; m.N = (sel == 0 || sel == 2) ? 2 * FH : (sel == 4 ? PW : D); m.kind = (sel == 0 || sel == 2) ? 1 : (sel == 4 ? 2 : 3);
;     tt = it - (sel == 0 ? 0 : sel == 1 ? O1 : sel == 2 ? O2 : sel == 3 ? O3 : sel == 4 ? O4 : sel == 5 ? O5 : sel == 6 ? O6 : O7);
; }
; __device__ __forceinline__ void convert_layer(const Args& A, Frame& F, int l) {
;     refresh(F);
;     constexpr int NT = 2 * 16 * 44 + 2 * 44 * 8 + 16 * 56 + 3 * 16 * 8;
;     const int nmy = (NT - F.bid + F.G - 1) / F.G;
;     f32x4 v[4];
;     { CvtMat m; int tt; cvt_pick(A, F, l, F.bid, m, tt); cvt_load(F, m, tt, v); }
.LBB0_552:
	s_and_b64 vcc, exec, s[4:5]
	s_mov_b32 s52, 0x3f2aaaab
	s_mov_b32 s33, 0x800000
	s_cbranch_vccz .LBB0_698
	s_cmp_eq_u32 s27, 0
	s_cselect_b64 s[6:7], -1, 0
	s_cmp_lg_u32 s27, 0
	s_cselect_b64 s[4:5], -1, 0
	s_cmp_lt_i32 s86, 13
	s_cselect_b64 s[8:9], -1, 0
	s_or_b64 s[4:5], s[8:9], s[4:5]
	s_and_b64 vcc, exec, s[4:5]
	s_cbranch_vccnz .LBB0_691
	s_cmpk_lg_i32 s34, 0x100
	s_cbranch_scc1 .Lcb_keep
	s_mov_b32 s98, s38
	s_mov_b32 s99, s34
	s_mov_b32 s32, 1
	s_min_u32 s100, s38, 64
	s_mul_i32 s38, s38, 13
	s_add_i32 s38, s38, s100
.Lcb_keep:
	s_cmpk_gt_i32 s38, 0x2bf
	s_cselect_b64 s[4:5], -1, 0
	s_cmpk_gt_i32 s38, 0x41f
	v_cndmask_b32_e64 v0, 0, 1, s[4:5]
	s_cselect_b64 s[4:5], -1, 0
	s_cmpk_gt_i32 s38, 0x6df
	v_cndmask_b32_e64 v2, 0, 1, s[4:5]
	s_cselect_b64 s[4:5], -1, 0
	v_readfirstlane_b32 s2, v0
	v_readfirstlane_b32 s8, v2
	s_cmp_lg_u64 s[4:5], 0
	s_addc_u32 s2, s2, s8
	s_cmpk_gt_i32 s38, 0x83f
	s_cselect_b64 s[4:5], -1, 0
	s_cmpk_gt_i32 s38, 0xbbf
	v_cndmask_b32_e64 v0, 0, 1, s[4:5]
	s_cselect_b64 s[4:5], -1, 0
	v_readfirstlane_b32 s8, v0
	s_cmp_lg_u64 s[4:5], 0
	s_addc_u32 s2, s2, s8
	s_cmpk_gt_i32 s38, 0xc3f
	s_cselect_b64 s[4:5], -1, 0
	s_cmpk_gt_i32 s38, 0xcbf
	v_cndmask_b32_e64 v0, 0, 1, s[4:5]
	s_cselect_b64 s[4:5], -1, 0
	v_readfirstlane_b32 s8, v0
	s_cmp_lg_u64 s[4:5], 0
	s_addc_u32 s2, s2, s8
	s_cmp_eq_u32 s2, 0
	s_cselect_b64 s[12:13], -1, 0
	s_cmp_eq_u32 s2, 6
	s_cselect_b64 s[10:11], -1, 0
	v_mov_b32_e32 v0, v138
	s_mov_b32 s8, 7
	s_and_b64 vcc, exec, s[12:13]
	s_cbranch_vccnz .LBB0_572
	s_cmp_lt_i32 s2, 3
	s_mov_b64 s[4:5], -1
	s_cbranch_scc1 .LBB0_569
	s_cmp_lt_i32 s2, 4
	s_cbranch_scc1 .LBB0_566
	s_cmp_lt_i32 s2, 5
	s_cbranch_scc1 .LBB0_563
	s_cmp_lg_u32 s2, 5
	s_cbranch_scc0 .LBB0_560
	s_and_b64 s[4:5], s[10:11], exec
	s_cselect_b32 s8, 19, 20
	s_mov_b64 s[4:5], 0

; __device__ __forceinline__ void refresh(Frame& F) { int t = threadIdx.x; asm volatile("" : "+v"(t)); F.tid = t; F.lane = t & 63; F.wave = __builtin_amdgcn_readfirstlane(t >> 6); }
; __device__ __forceinline__ void convert_layer(const Args& A, Frame& F, int l) {
;     refresh(F);
;     constexpr int NT = 2 * 16 * 44 + 2 * 44 * 8 + 16 * 56 + 3 * 16 * 8;
;     const int nmy = (NT - F.bid + F.G - 1) / F.G;
;     f32x4 v[4];
;     { CvtMat m; int tt; cvt_pick(A, F, l, F.bid, m, tt); cvt_load(F, m, tt, v); }
;     for (int j = 0; j < nmy; ++j) {
;         const int it = F.bid + j * F.G, itn = (j + 1 < nmy) ? it + F.G : it;
;         f32x4 vn[4];
;         { CvtMat mn; int ttn; cvt_pick(A, F, l, itn, mn, ttn); cvt_load(F, mn, ttn, vn); }
.LBB0_605:
	s_abs_i32 s2, s34
	v_cvt_f32_u32_e32 v3, s2
	s_sub_i32 s10, s34, s38
	s_add_i32 s11, s10, 0xd3f
	s_sub_i32 s10, 0xfffff2c1, s10
	v_rcp_iflag_f32_e32 v3, v3
	s_xor_b32 s13, s11, s34
	s_sub_i32 s12, 0, s2
	s_max_i32 s10, s11, s10
	v_mul_f32_e32 v3, 0x4f7ffffe, v3
	v_cvt_u32_f32_e32 v3, v3
	s_ashr_i32 s11, s13, 31
	v_readfirstlane_b32 s13, v3
	s_mul_i32 s12, s12, s13
	s_mul_hi_u32 s12, s13, s12
	s_add_i32 s13, s13, s12
	s_mul_hi_u32 s12, s10, s13
	s_mul_i32 s13, s12, s2
	s_sub_i32 s10, s10, s13
	s_add_i32 s15, s12, 1
	s_sub_i32 s13, s10, s2
	s_cmp_ge_u32 s10, s2
	s_cselect_b32 s12, s15, s12
	s_cselect_b32 s10, s13, s10
	s_add_i32 s13, s12, 1
	s_cmp_ge_u32 s10, s2
	s_cselect_b32 s2, s13, s12
	s_xor_b32 s2, s2, s11
	s_sub_i32 s2, s2, s11
	s_cmp_lt_i32 s2, 1
	s_cbranch_scc1 .LBB0_691
	s_cmp_eq_u32 s32, 1
	s_cbranch_scc0 .Lcb_keep2
	s_cmp_lt_u32 s98, 64
	s_cselect_b32 s2, 14, 13
	s_mov_b32 s34, 1
.Lcb_keep2:
	s_mul_hi_u32 s11, s4, s44
	s_mul_i32 s10, s4, s44
	s_lshl_b64 s[10:11], s[10:11], 2
	v_ashrrev_i32_e32 v35, 5, v0
	s_waitcnt lgkmcnt(0)
	s_add_u32 s8, s8, s10
	v_lshl_add_u32 v14, s14, 6, v35
	s_addc_u32 s9, s9, s11
	v_mad_i64_i32 v[4:5], s[10:11], v14, s5, 0
	v_ashrrev_i32_e32 v3, 31, v2
	v_lshl_add_u64 v[4:5], v[4:5], 2, s[8:9]
	v_lshlrev_b64 v[10:11], 2, v[2:3]
	v_lshl_add_u64 v[2:3], v[4:5], 0, v[10:11]
	v_add_u32_e32 v4, 16, v14
	v_add_u32_e32 v12, 32, v14
	v_add_u32_e32 v14, 48, v14
	v_mad_i64_i32 v[4:5], s[10:11], s5, v4, 0
	v_mad_i64_i32 v[12:13], s[10:11], s5, v12, 0
	v_mad_i64_i32 v[14:15], s[4:5], s5, v14, 0
	v_lshl_add_u64 v[4:5], v[4:5], 2, s[8:9]
	v_lshl_add_u64 v[12:13], v[12:13], 2, s[8:9]
	v_lshl_add_u64 v[14:15], v[14:15], 2, s[8:9]
	v_lshl_add_u64 v[6:7], v[4:5], 0, v[10:11]
	v_lshl_add_u64 v[12:13], v[12:13], 0, v[10:11]
	v_lshl_add_u64 v[14:15], v[14:15], 0, v[10:11]
	global_load_dwordx4 v[2:5], v[2:3], off
	s_nop 0
	global_load_dwordx4 v[6:9], v[6:7], off
	s_nop 0
	global_load_dwordx4 v[10:13], v[12:13], off
	s_nop 0
	global_load_dwordx4 v[14:17], v[14:15], off
	v_lshlrev_b32_e32 v22, 4, v0
	v_and_b32_e32 v22, 48, v22
	v_ashrrev_i32_e32 v36, 2, v0
	v_mul_u32_u24_e32 v25, 0x204, v22
	v_and_b32_e32 v0, -4, v0
	v_add3_u32 v37, 0, v25, v0
	v_lshrrev_b32_e32 v0, 1, v18
	s_movk_i32 s4, 0x204
	v_and_b32_e32 v0, 16, v0
	v_lshl_add_u32 v23, v34, 2, 0
	v_mul_lo_u32 v24, v35, s4
	v_and_or_b32 v38, v21, 32, v0
	v_and_b32_e32 v0, 0x60, v18
	v_or_b32_e32 v39, v20, v19
	v_or3_b32 v40, v0, v19, v20
	s_mov_b32 s20, 0
	v_add_u32_e32 v41, v23, v24
	v_lshlrev_b32_e32 v0, 1, v22
	s_mov_b32 s26, s38
	s_branch .LBB0_608

; __device__ __forceinline__ void refresh(Frame& F) { int t = threadIdx.x; asm volatile("" : "+v"(t)); F.tid = t; F.lane = t & 63; F.wave = __builtin_amdgcn_readfirstlane(t >> 6); }
; __device__ __forceinline__ void convert_layer(const Args& A, Frame& F, int l) {
;     refresh(F);
;     constexpr int NT = 2 * 16 * 44 + 2 * 44 * 8 + 16 * 56 + 3 * 16 * 8;
;     const int nmy = (NT - F.bid + F.G - 1) / F.G;
;     f32x4 v[4];
;     { CvtMat m; int tt; cvt_pick(A, F, l, F.bid, m, tt); cvt_load(F, m, tt, v); }
;     for (int j = 0; j < nmy; ++j) {
;         const int it = F.bid + j * F.G, itn = (j + 1 < nmy) ? it + F.G : it;
;         f32x4 vn[4];
;         { CvtMat mn; int ttn; cvt_pick(A, F, l, itn, mn, ttn); cvt_load(F, mn, ttn, vn); }
;         { CvtMat m; int tt; cvt_pick(A, F, l, it, m, tt); cvt_store(F, m, tt, v); }
; #pragma unroll
;         for (int i = 0; i < 4; ++i) v[i] = vn[i];
;     }
; }
.LBB0_691:
	s_cmp_eq_u32 s32, 1
	s_cbranch_scc0 .Lcb_keep3
	s_mov_b32 s38, s98
	s_mov_b32 s34, s99
	s_mov_b32 s32, 0
